# NSA lean loop back edge: fast tail tests only the pair counter and re-enters the lean head directly, skipping the mode / UNSET dispatch chain
# baseline (speedup 1.0000x reference)
.Lm2_head:
	s_add_i32 s21, s38, s45
	s_and_b32 s20, s45, 2
	s_add_i32 s54, s54, 1
	s_mov_b64 s[94:95], 0
	s_lshl_b32 s30, s20, 13
	v_add_u32_e32 v8, s30, v169
	ds_read_b128 v[10:13], v8
	ds_read_b128 v[14:17], v8 offset:512
	ds_read_b128 v[174:177], v8 offset:2048
	ds_read_b128 v[178:181], v8 offset:2560
	ds_read_b128 v[182:185], v8 offset:4096
	ds_read_b128 v[186:189], v8 offset:4608
	ds_read_b128 v[228:231], v8 offset:6144
	ds_read_b128 v[232:235], v8 offset:6656
	v_add_u32_e32 v3, s30, v193
	s_lshr_b32 s0, s21, 5
	s_cmp_lt_u32 s0, 2
	s_cselect_b64 s[98:99], -1, 0
	s_bitcmp1_b32 s0, 0
	s_cselect_b64 s[0:1], -1, 0
	s_and_b32 s28, s21, 31
	v_cndmask_b32_e64 v5, v130, v131, s[0:1]
	v_cndmask_b32_e64 v6, v132, v133, s[0:1]
	v_cndmask_b32_e64 v5, v6, v5, s[98:99]
	v_lshrrev_b32_e32 v5, s28, v5
	v_and_b32_e32 v6, 1, v5
	v_bfe_u32 v9, v5, 1, 1
	v_xor_b32_e32 v7, 0x80000000, v222
	v_cmp_eq_u32_e32 vcc, 1, v6
	v_cmp_eq_u32_e64 s[98:99], 1, v9
	v_add_f32_e32 v4, v7, v201
	s_cmp_lg_u64 vcc, 0
	s_cselect_b32 s55, 1, 0
	v_cndmask_b32_e32 v82, v4, v7, vcc
	v_cndmask_b32_e64 v50, v4, v7, s[98:99]
	s_cmp_lg_u64 s[98:99], 0
	s_cselect_b32 s0, 2, 0
	s_or_b32 s55, s55, s0
	s_cmp_eq_u32 s55, 3
	s_cbranch_scc0 .Lm2_partial
	v_mov_b32_e32 v83, v82
	v_mov_b64_e32 v[84:85], v[82:83]
	v_mov_b64_e32 v[86:87], v[82:83]
	v_mov_b64_e32 v[88:89], v[82:83]
	v_mov_b64_e32 v[90:91], v[82:83]
	v_mov_b64_e32 v[92:93], v[82:83]
	v_mov_b64_e32 v[94:95], v[82:83]
	v_mov_b64_e32 v[96:97], v[82:83]
	v_mov_b32_e32 v51, v50
	v_mov_b64_e32 v[52:53], v[50:51]
	s_waitcnt lgkmcnt(7)
	v_mfma_f32_32x32x16_bf16 v[98:113], v[10:13], v[114:117], v[82:97]
	ds_read_b128 v[10:13], v8 offset:8192
	v_mov_b64_e32 v[54:55], v[50:51]
	v_mov_b64_e32 v[56:57], v[50:51]
	v_mov_b64_e32 v[58:59], v[50:51]
	v_mov_b64_e32 v[60:61], v[50:51]
	v_mov_b64_e32 v[62:63], v[50:51]
	s_waitcnt lgkmcnt(7)
	v_mfma_f32_32x32x16_bf16 v[82:97], v[14:17], v[114:117], v[82:97]
	ds_read_b128 v[14:17], v8 offset:8704
	v_mov_b64_e32 v[64:65], v[50:51]
	s_add_i32 s0, s21, 2
	s_ashr_i32 s1, s0, 31
	s_lshl_b64 s[0:1], s[0:1], 6
	s_add_u32 s0, s0, s84
	s_waitcnt lgkmcnt(7)
	v_mfma_f32_32x32x16_bf16 v[98:113], v[174:177], v[118:121], v[98:113]
	ds_read_b128 v[174:177], v8 offset:10240
	s_addc_u32 s1, s1, s85
	s_lshl_b64 s[0:1], s[0:1], 7
	s_add_u32 s28, s86, s0
	s_addc_u32 s29, s87, s1
	s_sub_i32 s31, s37, s30
	s_waitcnt lgkmcnt(7)
	v_mfma_f32_32x32x16_bf16 v[82:97], v[178:181], v[118:121], v[82:97]
	ds_read_b128 v[178:181], v8 offset:10752
	s_add_i32 s31, s31, 0x4000
	v_lshlrev_b32_e32 v5, 7, v138
	s_mov_b32 m0, s31
	s_movk_i32 s30, 0x80
	global_load_lds_dwordx4 v5, s[28:29]
	s_waitcnt lgkmcnt(7)
	v_mfma_f32_32x32x16_bf16 v[98:113], v[182:185], v[122:125], v[98:113]
	ds_read_b128 v[182:185], v8 offset:12288
	v_mad_u64_u32 v[226:227], vcc, v168, s30, v[134:135]
	s_add_i32 s31, s31, 0x8000
	v_lshl_add_u64 v[6:7], v[226:227], 0, s[0:1]
	s_mov_b32 m0, s31
	s_cmp_lt_i32 s45, s44
	s_waitcnt lgkmcnt(7)
	v_mfma_f32_32x32x16_bf16 v[82:97], v[186:189], v[122:125], v[82:97]
	ds_read_b128 v[186:189], v8 offset:12800
	global_load_lds_dwordx4 v[6:7], off
	s_cselect_b32 s98, 0x2000, 0
	s_add_u32 s28, s28, s98
	s_waitcnt lgkmcnt(7)
	v_mfma_f32_32x32x16_bf16 v[98:113], v[228:231], v[126:129], v[98:113]
	ds_read_b128 v[228:231], v8 offset:14336
	s_addc_u32 s29, s29, 0
	s_add_u32 s0, s0, s98
	s_addc_u32 s1, s1, 0
	s_sub_i32 s31, s31, 0x6000
	s_mov_b32 m0, s31
	s_waitcnt lgkmcnt(7)
	v_mfma_f32_32x32x16_bf16 v[82:97], v[232:235], v[126:129], v[82:97]
	ds_read_b128 v[232:235], v8 offset:14848
	v_lshl_add_u64 v[6:7], v[226:227], 0, s[0:1]
	global_load_lds_dwordx4 v5, s[28:29]
	s_add_i32 s31, s31, 0x8000
	s_waitcnt lgkmcnt(7)
	v_mfma_f32_32x32x16_bf16 v[66:81], v[10:13], v[114:117], v[50:65]
	ds_read_b64_tr_b16 v[10:11], v3 offset:32768
	ds_read_b64_tr_b16 v[12:13], v3 offset:33280
	s_mov_b32 m0, s31
	s_nop 0
	global_load_lds_dwordx4 v[6:7], off
	s_waitcnt lgkmcnt(8)
	v_mfma_f32_32x32x16_bf16 v[50:65], v[14:17], v[114:117], v[50:65]
	ds_read_b64_tr_b16 v[14:15], v3 offset:36864
	ds_read_b64_tr_b16 v[16:17], v3 offset:37376
	v_exp_f32_e32 v98, v98
	v_exp_f32_e32 v99, v99
	v_exp_f32_e32 v100, v100
	s_waitcnt lgkmcnt(9)
	v_mfma_f32_32x32x16_bf16 v[66:81], v[174:177], v[118:121], v[66:81]
	ds_read_b64_tr_b16 v[174:175], v3 offset:33792
	ds_read_b64_tr_b16 v[176:177], v3 offset:34304
	v_exp_f32_e32 v101, v101
	v_exp_f32_e32 v102, v102
	v_exp_f32_e32 v103, v103
	s_waitcnt lgkmcnt(10)
	v_mfma_f32_32x32x16_bf16 v[50:65], v[178:181], v[118:121], v[50:65]
	ds_read_b64_tr_b16 v[178:179], v3 offset:37888
	ds_read_b64_tr_b16 v[180:181], v3 offset:38400
	v_exp_f32_e32 v104, v104
	v_exp_f32_e32 v105, v105
	v_cvt_pk_bf16_f32 v236, v98, v99
	s_waitcnt lgkmcnt(11)
	v_mfma_f32_32x32x16_bf16 v[66:81], v[182:185], v[122:125], v[66:81]
	ds_read_b64_tr_b16 v[182:183], v3 offset:34816
	ds_read_b64_tr_b16 v[184:185], v3 offset:35328
	v_cvt_pk_bf16_f32 v237, v100, v101
	v_cvt_pk_bf16_f32 v238, v102, v103
	v_cvt_pk_bf16_f32 v239, v104, v105
	v_exp_f32_e32 v106, v106
	s_waitcnt lgkmcnt(12)
	v_mfma_f32_32x32x16_bf16 v[50:65], v[186:189], v[122:125], v[50:65]
	ds_read_b64_tr_b16 v[186:187], v3 offset:38912
	ds_read_b64_tr_b16 v[188:189], v3 offset:39424
	v_exp_f32_e32 v107, v107
	v_exp_f32_e32 v108, v108
	v_exp_f32_e32 v109, v109
	s_waitcnt lgkmcnt(13)
	v_mfma_f32_32x32x16_bf16 v[66:81], v[228:231], v[126:129], v[66:81]
	ds_read_b64_tr_b16 v[228:229], v3 offset:35840
	ds_read_b64_tr_b16 v[230:231], v3 offset:36352
	v_exp_f32_e32 v110, v110
	v_exp_f32_e32 v111, v111
	v_exp_f32_e32 v112, v112
	s_waitcnt lgkmcnt(14)
	v_mfma_f32_32x32x16_bf16 v[50:65], v[232:235], v[126:129], v[50:65]
	s_waitcnt lgkmcnt(13)
	ds_read_b64_tr_b16 v[232:233], v3 offset:39936
	ds_read_b64_tr_b16 v[234:235], v3 offset:40448
	v_exp_f32_e32 v113, v113
	v_cvt_pk_bf16_f32 v240, v106, v107
	v_cvt_pk_bf16_f32 v241, v108, v109
	v_cvt_pk_bf16_f32 v242, v110, v111
	s_waitcnt lgkmcnt(14)
	v_mfma_f32_32x32x16_bf16 v[34:49], v[236:239], v[10:13], v[34:49]
	s_waitcnt lgkmcnt(13)
	ds_read_b64_tr_b16 v[10:11], v3 offset:40960
	ds_read_b64_tr_b16 v[12:13], v3 offset:41472
	v_cvt_pk_bf16_f32 v243, v112, v113
	v_exp_f32_e32 v82, v82
	v_exp_f32_e32 v83, v83
	s_waitcnt lgkmcnt(14)
	v_mfma_f32_32x32x16_bf16 v[18:33], v[236:239], v[14:17], v[18:33]
	s_waitcnt lgkmcnt(13)
	ds_read_b64_tr_b16 v[14:15], v3 offset:45056
	ds_read_b64_tr_b16 v[16:17], v3 offset:45568
	v_exp_f32_e32 v84, v84
	v_exp_f32_e32 v85, v85
	v_exp_f32_e32 v86, v86
	s_waitcnt lgkmcnt(14)
	v_mfma_f32_32x32x16_bf16 v[34:49], v[240:243], v[174:177], v[34:49]
	s_waitcnt lgkmcnt(13)
	ds_read_b64_tr_b16 v[174:175], v3 offset:41984
	ds_read_b64_tr_b16 v[176:177], v3 offset:42496
	v_exp_f32_e32 v87, v87
	v_exp_f32_e32 v88, v88
	v_exp_f32_e32 v89, v89
	s_waitcnt lgkmcnt(14)
	v_mfma_f32_32x32x16_bf16 v[18:33], v[240:243], v[178:181], v[18:33]
	s_waitcnt lgkmcnt(13)
	ds_read_b64_tr_b16 v[178:179], v3 offset:46080
	ds_read_b64_tr_b16 v[180:181], v3 offset:46592
	v_cvt_pk_bf16_f32 v244, v82, v83
	v_cvt_pk_bf16_f32 v245, v84, v85
	v_cvt_pk_bf16_f32 v246, v86, v87
	v_cvt_pk_bf16_f32 v247, v88, v89
	v_exp_f32_e32 v90, v90
	v_exp_f32_e32 v91, v91
	s_waitcnt lgkmcnt(14)
	v_mfma_f32_32x32x16_bf16 v[34:49], v[244:247], v[182:185], v[34:49]
	s_waitcnt lgkmcnt(13)
	ds_read_b64_tr_b16 v[182:183], v3 offset:43008
	ds_read_b64_tr_b16 v[184:185], v3 offset:43520
	v_exp_f32_e32 v92, v92
	v_exp_f32_e32 v93, v93
	v_exp_f32_e32 v94, v94
	s_waitcnt lgkmcnt(14)
	v_mfma_f32_32x32x16_bf16 v[18:33], v[244:247], v[186:189], v[18:33]
	s_waitcnt lgkmcnt(13)
	ds_read_b64_tr_b16 v[186:187], v3 offset:47104
	ds_read_b64_tr_b16 v[188:189], v3 offset:47616
	v_exp_f32_e32 v95, v95
	v_exp_f32_e32 v96, v96
	v_exp_f32_e32 v97, v97
	v_cvt_pk_bf16_f32 v248, v90, v91
	v_cvt_pk_bf16_f32 v249, v92, v93
	v_cvt_pk_bf16_f32 v250, v94, v95
	v_cvt_pk_bf16_f32 v251, v96, v97
	v_exp_f32_e32 v66, v66
	v_exp_f32_e32 v67, v67
	s_waitcnt lgkmcnt(14)
	v_mfma_f32_32x32x16_bf16 v[34:49], v[248:251], v[228:231], v[34:49]
	s_waitcnt lgkmcnt(13)
	ds_read_b64_tr_b16 v[228:229], v3 offset:44032
	ds_read_b64_tr_b16 v[230:231], v3 offset:44544
	v_exp_f32_e32 v68, v68
	v_exp_f32_e32 v69, v69
	v_exp_f32_e32 v70, v70
	s_waitcnt lgkmcnt(14)
	v_mfma_f32_32x32x16_bf16 v[18:33], v[248:251], v[232:235], v[18:33]
	s_waitcnt lgkmcnt(13)
	ds_read_b64_tr_b16 v[232:233], v3 offset:48128
	ds_read_b64_tr_b16 v[234:235], v3 offset:48640
	v_exp_f32_e32 v71, v71
	v_exp_f32_e32 v72, v72
	v_exp_f32_e32 v73, v73
	v_cvt_pk_bf16_f32 v236, v66, v67
	v_cvt_pk_bf16_f32 v237, v68, v69
	v_cvt_pk_bf16_f32 v238, v70, v71
	v_cvt_pk_bf16_f32 v239, v72, v73
	v_exp_f32_e32 v74, v74
	v_exp_f32_e32 v75, v75
	s_waitcnt lgkmcnt(14)
	v_mfma_f32_32x32x16_bf16 v[34:49], v[236:239], v[10:13], v[34:49]
	v_exp_f32_e32 v76, v76
	v_exp_f32_e32 v77, v77
	v_exp_f32_e32 v78, v78
	s_waitcnt lgkmcnt(12)
	v_mfma_f32_32x32x16_bf16 v[18:33], v[236:239], v[14:17], v[18:33]
	v_exp_f32_e32 v79, v79
	v_exp_f32_e32 v80, v80
	v_exp_f32_e32 v81, v81
	v_cvt_pk_bf16_f32 v240, v74, v75
	v_cvt_pk_bf16_f32 v241, v76, v77
	v_cvt_pk_bf16_f32 v242, v78, v79
	v_cvt_pk_bf16_f32 v243, v80, v81
	v_exp_f32_e32 v50, v50
	v_exp_f32_e32 v51, v51
	s_waitcnt lgkmcnt(10)
	v_mfma_f32_32x32x16_bf16 v[34:49], v[240:243], v[174:177], v[34:49]
	v_exp_f32_e32 v52, v52
	v_exp_f32_e32 v53, v53
	v_exp_f32_e32 v54, v54
	s_waitcnt lgkmcnt(8)
	v_mfma_f32_32x32x16_bf16 v[18:33], v[240:243], v[178:181], v[18:33]
	v_exp_f32_e32 v55, v55
	v_exp_f32_e32 v56, v56
	v_exp_f32_e32 v57, v57
	v_cvt_pk_bf16_f32 v244, v50, v51
	v_cvt_pk_bf16_f32 v245, v52, v53
	v_cvt_pk_bf16_f32 v246, v54, v55
	v_cvt_pk_bf16_f32 v247, v56, v57
	v_exp_f32_e32 v58, v58
	v_exp_f32_e32 v59, v59
	s_waitcnt lgkmcnt(6)
	v_mfma_f32_32x32x16_bf16 v[34:49], v[244:247], v[182:185], v[34:49]
	v_exp_f32_e32 v60, v60
	v_exp_f32_e32 v61, v61
	v_exp_f32_e32 v62, v62
	s_waitcnt lgkmcnt(4)
	v_mfma_f32_32x32x16_bf16 v[18:33], v[244:247], v[186:189], v[18:33]
	v_exp_f32_e32 v63, v63
	v_exp_f32_e32 v64, v64
	v_exp_f32_e32 v65, v65
	v_cvt_pk_bf16_f32 v248, v58, v59
	v_cvt_pk_bf16_f32 v249, v60, v61
	v_cvt_pk_bf16_f32 v250, v62, v63
	v_cvt_pk_bf16_f32 v251, v64, v65
	v_pk_add_f32 v[4:5], v[98:99], v[100:101]
	v_pk_add_f32 v[6:7], v[82:83], v[84:85]
	s_waitcnt lgkmcnt(2)
	v_mfma_f32_32x32x16_bf16 v[34:49], v[248:251], v[228:231], v[34:49]
	v_pk_add_f32 v[4:5], v[4:5], v[102:103]
	v_pk_add_f32 v[6:7], v[6:7], v[86:87]
	v_pk_add_f32 v[4:5], v[4:5], v[104:105]
	v_pk_add_f32 v[6:7], v[6:7], v[88:89]
	v_pk_add_f32 v[4:5], v[4:5], v[106:107]
	s_waitcnt lgkmcnt(0)
	v_mfma_f32_32x32x16_bf16 v[18:33], v[248:251], v[232:235], v[18:33]
	v_pk_add_f32 v[6:7], v[6:7], v[90:91]
	v_pk_add_f32 v[4:5], v[4:5], v[108:109]
	v_pk_add_f32 v[6:7], v[6:7], v[92:93]
	v_pk_add_f32 v[4:5], v[4:5], v[110:111]
	v_pk_add_f32 v[6:7], v[6:7], v[94:95]
	v_pk_add_f32 v[4:5], v[4:5], v[112:113]
	v_pk_add_f32 v[6:7], v[6:7], v[96:97]
	v_add_f32_e32 v6, v6, v7
	v_add_f32_e32 v4, v4, v5
	v_add_f32_e32 v4, v6, v4
	v_mov_b32_e32 v5, v4
	v_add_f32_e32 v225, v225, v4
	v_pk_add_f32 v[4:5], v[66:67], v[68:69]
	v_pk_add_f32 v[6:7], v[50:51], v[52:53]
	v_pk_add_f32 v[4:5], v[4:5], v[70:71]
	v_pk_add_f32 v[6:7], v[6:7], v[54:55]
	v_pk_add_f32 v[4:5], v[4:5], v[72:73]
	v_pk_add_f32 v[6:7], v[6:7], v[56:57]
	v_pk_add_f32 v[4:5], v[4:5], v[74:75]
	v_pk_add_f32 v[6:7], v[6:7], v[58:59]
	v_pk_add_f32 v[4:5], v[4:5], v[76:77]
	v_pk_add_f32 v[6:7], v[6:7], v[60:61]
	v_pk_add_f32 v[4:5], v[4:5], v[78:79]
	v_pk_add_f32 v[6:7], v[6:7], v[62:63]
	v_pk_add_f32 v[4:5], v[4:5], v[80:81]
	v_pk_add_f32 v[6:7], v[6:7], v[64:65]
	v_add_f32_e32 v6, v6, v7
	v_add_f32_e32 v4, v4, v5
	v_add_f32_e32 v4, v6, v4
	v_add_f32_e32 v225, v225, v4
	s_mov_b64 s[20:21], 0
	s_mov_b32 s30, 0x437f0000
	v_cmp_nge_f32_e32 vcc, s30, v5
	v_cmp_nge_f32_e64 s[98:99], s30, v4
	s_or_b64 s[98:99], vcc, s[98:99]
	s_cbranch_scc1 .Lm2_rare_full
	s_waitcnt vmcnt(0) lgkmcnt(0)
	s_barrier
	s_add_i32 s45, s45, 2
	s_add_i32 s98, s54, 1
	s_cmp_lt_i32 s98, s53
	s_cbranch_scc1 .Lm2_head
	s_branch .LBB0_1463

.Lm2_st:
	v_mov_b32_e32 v83, v82
	v_mov_b64_e32 v[84:85], v[82:83]
	v_mov_b64_e32 v[86:87], v[82:83]
	v_mov_b64_e32 v[88:89], v[82:83]
	v_mov_b64_e32 v[90:91], v[82:83]
	v_mov_b64_e32 v[92:93], v[82:83]
	v_mov_b64_e32 v[94:95], v[82:83]
	v_mov_b64_e32 v[96:97], v[82:83]
	s_add_i32 s0, s21, 2
	s_ashr_i32 s1, s0, 31
	s_waitcnt lgkmcnt(7)
	v_mfma_f32_32x32x16_bf16 v[98:113], v[10:13], v[114:117], v[82:97]
	ds_read_b64_tr_b16 v[10:11], v3 offset:32768
	ds_read_b64_tr_b16 v[12:13], v3 offset:33280
	s_lshl_b64 s[0:1], s[0:1], 6
	s_add_u32 s0, s0, s84
	s_addc_u32 s1, s1, s85
	s_lshl_b64 s[0:1], s[0:1], 7
	s_add_u32 s28, s86, s0
	s_waitcnt lgkmcnt(8)
	v_mfma_f32_32x32x16_bf16 v[82:97], v[14:17], v[114:117], v[82:97]
	ds_read_b64_tr_b16 v[14:15], v3 offset:36864
	ds_read_b64_tr_b16 v[16:17], v3 offset:37376
	s_addc_u32 s29, s87, s1
	s_sub_i32 s31, s37, s30
	s_add_i32 s31, s31, 0x4000
	v_lshlrev_b32_e32 v5, 7, v138
	s_mov_b32 m0, s31
	s_waitcnt lgkmcnt(9)
	v_mfma_f32_32x32x16_bf16 v[98:113], v[174:177], v[118:121], v[98:113]
	ds_read_b64_tr_b16 v[174:175], v3 offset:33792
	ds_read_b64_tr_b16 v[176:177], v3 offset:34304
	s_movk_i32 s30, 0x80
	global_load_lds_dwordx4 v5, s[28:29]
	v_mad_u64_u32 v[226:227], vcc, v168, s30, v[134:135]
	s_waitcnt lgkmcnt(10)
	v_mfma_f32_32x32x16_bf16 v[82:97], v[178:181], v[118:121], v[82:97]
	ds_read_b64_tr_b16 v[178:179], v3 offset:37888
	ds_read_b64_tr_b16 v[180:181], v3 offset:38400
	s_add_i32 s31, s31, 0x8000
	v_lshl_add_u64 v[6:7], v[226:227], 0, s[0:1]
	s_mov_b32 m0, s31
	s_cmp_lt_i32 s45, s44
	global_load_lds_dwordx4 v[6:7], off
	s_waitcnt lgkmcnt(11)
	v_mfma_f32_32x32x16_bf16 v[98:113], v[182:185], v[122:125], v[98:113]
	ds_read_b64_tr_b16 v[182:183], v3 offset:34816
	ds_read_b64_tr_b16 v[184:185], v3 offset:35328
	s_cselect_b32 s98, 0x2000, 0
	s_add_u32 s28, s28, s98
	s_addc_u32 s29, s29, 0
	s_add_u32 s0, s0, s98
	s_addc_u32 s1, s1, 0
	s_waitcnt lgkmcnt(12)
	v_mfma_f32_32x32x16_bf16 v[82:97], v[186:189], v[122:125], v[82:97]
	ds_read_b64_tr_b16 v[186:187], v3 offset:38912
	ds_read_b64_tr_b16 v[188:189], v3 offset:39424
	s_sub_i32 s31, s31, 0x6000
	s_mov_b32 m0, s31
	v_lshl_add_u64 v[6:7], v[226:227], 0, s[0:1]
	global_load_lds_dwordx4 v5, s[28:29]
	s_waitcnt lgkmcnt(13)
	v_mfma_f32_32x32x16_bf16 v[98:113], v[228:231], v[126:129], v[98:113]
	ds_read_b64_tr_b16 v[228:229], v3 offset:35840
	ds_read_b64_tr_b16 v[230:231], v3 offset:36352
	s_add_i32 s31, s31, 0x8000
	s_mov_b32 m0, s31
	s_nop 0
	global_load_lds_dwordx4 v[6:7], off
	s_waitcnt lgkmcnt(14)
	v_mfma_f32_32x32x16_bf16 v[82:97], v[232:235], v[126:129], v[82:97]
	s_waitcnt lgkmcnt(13)
	ds_read_b64_tr_b16 v[232:233], v3 offset:39936
	ds_read_b64_tr_b16 v[234:235], v3 offset:40448
	s_nop 0
	s_nop 0
	s_nop 0
	s_nop 0
	s_nop 0
	s_nop 0
	s_nop 0
	s_nop 0
	s_nop 0
	v_exp_f32_e32 v98, v98
	v_exp_f32_e32 v99, v99
	v_exp_f32_e32 v100, v100
	v_exp_f32_e32 v101, v101
	v_exp_f32_e32 v102, v102
	v_exp_f32_e32 v103, v103
	v_exp_f32_e32 v104, v104
	v_exp_f32_e32 v105, v105
	v_cvt_pk_bf16_f32 v236, v98, v99
	v_cvt_pk_bf16_f32 v237, v100, v101
	v_cvt_pk_bf16_f32 v238, v102, v103
	v_cvt_pk_bf16_f32 v239, v104, v105
	v_exp_f32_e32 v106, v106
	v_exp_f32_e32 v107, v107
	s_waitcnt lgkmcnt(14)
	v_mfma_f32_32x32x16_bf16 v[34:49], v[236:239], v[10:13], v[34:49]
	v_exp_f32_e32 v108, v108
	v_exp_f32_e32 v109, v109
	v_exp_f32_e32 v110, v110
	s_waitcnt lgkmcnt(12)
	v_mfma_f32_32x32x16_bf16 v[18:33], v[236:239], v[14:17], v[18:33]
	v_exp_f32_e32 v111, v111
	v_exp_f32_e32 v112, v112
	v_exp_f32_e32 v113, v113
	v_cvt_pk_bf16_f32 v240, v106, v107
	v_cvt_pk_bf16_f32 v241, v108, v109
	v_cvt_pk_bf16_f32 v242, v110, v111
	v_cvt_pk_bf16_f32 v243, v112, v113
	v_exp_f32_e32 v82, v82
	v_exp_f32_e32 v83, v83
	s_waitcnt lgkmcnt(10)
	v_mfma_f32_32x32x16_bf16 v[34:49], v[240:243], v[174:177], v[34:49]
	v_exp_f32_e32 v84, v84
	v_exp_f32_e32 v85, v85
	v_exp_f32_e32 v86, v86
	s_waitcnt lgkmcnt(8)
	v_mfma_f32_32x32x16_bf16 v[18:33], v[240:243], v[178:181], v[18:33]
	v_exp_f32_e32 v87, v87
	v_exp_f32_e32 v88, v88
	v_exp_f32_e32 v89, v89
	v_cvt_pk_bf16_f32 v244, v82, v83
	v_cvt_pk_bf16_f32 v245, v84, v85
	v_cvt_pk_bf16_f32 v246, v86, v87
	v_cvt_pk_bf16_f32 v247, v88, v89
	v_exp_f32_e32 v90, v90
	v_exp_f32_e32 v91, v91
	s_waitcnt lgkmcnt(6)
	v_mfma_f32_32x32x16_bf16 v[34:49], v[244:247], v[182:185], v[34:49]
	v_exp_f32_e32 v92, v92
	v_exp_f32_e32 v93, v93
	v_exp_f32_e32 v94, v94
	s_waitcnt lgkmcnt(4)
	v_mfma_f32_32x32x16_bf16 v[18:33], v[244:247], v[186:189], v[18:33]
	v_exp_f32_e32 v95, v95
	v_exp_f32_e32 v96, v96
	v_exp_f32_e32 v97, v97
	v_cvt_pk_bf16_f32 v248, v90, v91
	v_cvt_pk_bf16_f32 v249, v92, v93
	v_cvt_pk_bf16_f32 v250, v94, v95
	v_cvt_pk_bf16_f32 v251, v96, v97
	v_pk_add_f32 v[4:5], v[98:99], v[100:101]
	v_pk_add_f32 v[6:7], v[82:83], v[84:85]
	s_waitcnt lgkmcnt(2)
	v_mfma_f32_32x32x16_bf16 v[34:49], v[248:251], v[228:231], v[34:49]
	v_pk_add_f32 v[4:5], v[4:5], v[102:103]
	v_pk_add_f32 v[6:7], v[6:7], v[86:87]
	v_pk_add_f32 v[4:5], v[4:5], v[104:105]
	v_pk_add_f32 v[6:7], v[6:7], v[88:89]
	v_pk_add_f32 v[4:5], v[4:5], v[106:107]
	s_waitcnt lgkmcnt(0)
	v_mfma_f32_32x32x16_bf16 v[18:33], v[248:251], v[232:235], v[18:33]
	v_pk_add_f32 v[6:7], v[6:7], v[90:91]
	v_pk_add_f32 v[4:5], v[4:5], v[108:109]
	v_pk_add_f32 v[6:7], v[6:7], v[92:93]
	v_pk_add_f32 v[4:5], v[4:5], v[110:111]
	v_pk_add_f32 v[6:7], v[6:7], v[94:95]
	v_pk_add_f32 v[4:5], v[4:5], v[112:113]
	v_pk_add_f32 v[6:7], v[6:7], v[96:97]
	v_add_f32_e32 v6, v6, v7
	v_add_f32_e32 v4, v4, v5
	v_add_f32_e32 v4, v6, v4
	v_mov_b32_e32 v5, v4
	v_add_f32_e32 v225, v225, v4
	s_mov_b64 s[20:21], 0
	s_mov_b32 s30, 0x437f0000
	v_cmp_nge_f32_e32 vcc, s30, v5
	s_cmp_lg_u64 vcc, 0
	s_cbranch_scc1 .Lm2_rare_st
	s_waitcnt vmcnt(0) lgkmcnt(0)
	s_barrier
	s_add_i32 s45, s45, 2
	s_add_i32 s98, s54, 1
	s_cmp_lt_i32 s98, s53
	s_cbranch_scc1 .Lm2_head
	s_branch .LBB0_1463

.Lm2_none:
	s_add_i32 s0, s21, 2
	s_ashr_i32 s1, s0, 31
	s_lshl_b64 s[0:1], s[0:1], 6
	s_add_u32 s0, s0, s84
	s_addc_u32 s1, s1, s85
	s_lshl_b64 s[0:1], s[0:1], 7
	s_add_u32 s28, s86, s0
	s_addc_u32 s29, s87, s1
	s_sub_i32 s31, s37, s30
	s_add_i32 s31, s31, 0x4000
	v_lshlrev_b32_e32 v5, 7, v138
	s_mov_b32 m0, s31
	s_movk_i32 s30, 0x80
	global_load_lds_dwordx4 v5, s[28:29]
	v_mad_u64_u32 v[226:227], vcc, v168, s30, v[134:135]
	s_add_i32 s31, s31, 0x8000
	v_lshl_add_u64 v[6:7], v[226:227], 0, s[0:1]
	s_mov_b32 m0, s31
	s_cmp_lt_i32 s45, s44
	global_load_lds_dwordx4 v[6:7], off
	s_cselect_b32 s98, 0x2000, 0
	s_add_u32 s28, s28, s98
	s_addc_u32 s29, s29, 0
	s_add_u32 s0, s0, s98
	s_addc_u32 s1, s1, 0
	s_sub_i32 s31, s31, 0x6000
	s_mov_b32 m0, s31
	v_lshl_add_u64 v[6:7], v[226:227], 0, s[0:1]
	global_load_lds_dwordx4 v5, s[28:29]
	s_add_i32 s31, s31, 0x8000
	s_mov_b32 m0, s31
	s_nop 0
	global_load_lds_dwordx4 v[6:7], off
	s_waitcnt vmcnt(0) lgkmcnt(0)
	s_barrier
	s_add_i32 s45, s45, 2
	s_add_i32 s98, s54, 1
	s_cmp_lt_i32 s98, s53
	s_cbranch_scc1 .Lm2_head
	s_branch .LBB0_1463
